# attn-C: K tiles in a static 2-deep LDS ring (immediate offsets, no per-read address adds), scalar rescale flag, fewer LDS store address adds
# speedup vs baseline: 1.0029x; 1.0029x over previous
; __device__ __forceinline__ int tid_() { int t = (int)threadIdx.x; asm volatile("" : "+v"(t)); return t; }
; __device__ __forceinline__ int v_st(int k, int c) { const int kk = (k & ~0xC) | ((k & 4) << 1) | ((k & 8) >> 1); return ((kk >> 3) * 4 + (c >> 5)) * 512 + ((kk & 7) * 32 + (c & 31)) * 2; }
; __device__ __forceinline__ int v_rd_base(int lane) { return ((lane & 3) << 3) | (((lane >> 2) & 3) << 6) | (((lane >> 4) & 1) << 5) | (((lane >> 5) & 1) << 8); }
; __device__ __forceinline__ void attn_dense_body(const bf16_t* __restrict__ Qb, const bf16_t* __restrict__ Kh, const bf16_t* __restrict__ Vh,
;                                                 bf16_t* __restrict__ Ob, int seq, char* lds, int dry) {
;     const int tid = tid_(), wid = tid >> 6, lane = tid & 63, r32 = lane & 31, hi = lane >> 5;
;     bf16_t* V_lds = (bf16_t*)lds; bf16_t* K_lds = (bf16_t*)(lds + 3 * SHM_V);
;     float* ws = (float*)(lds + 3 * SHM_V + 3 * SHM_K) + wid * 64; float* li_l = ws; float* al_l = ws + 32;
;     float m_reg = -1e30f, l_reg = 0; f32x16 o[4] = {}; bf16x8 qr[8];
;     const bf16_t* Qw = Qb + (long)(wid * QBLK + r32) * LDQ + hi * 8;
; #pragma unroll
;     for (int d0 = 0; d0 < 8; ++d0) qr[d0] = *reinterpret_cast<const bf16x8*>(Qw + d0 * 16);
;     const int sr = tid >> 4, sc = (tid & 15) * 8, vst0 = v_st(sr, sc), vst1 = v_st(32 + sr, sc);
;     const int vb0 = (int)(uintptr_t)V_lds + v_rd_base(lane);
;     bf16x8 sv0[2], sv1[2], sk0[2], sk1[2];
;     ...
;     f32x16 pA0, pA1, pB0, pB1; float mnA, mnB, alA, alB; bf16x8 pa0, pa1, pa2, pa3; const int NT = seq / KVBLK;
;     SLOAD(0, 0); asm volatile("s_waitcnt vmcnt(0)" ::: "memory"); SWRITE(0, 0); __syncthreads();
;     qkt(pA0, pA1, K_lds, qr, r32, hi); partialSM(pA0, pA1, m_reg, mnA, alA);
; __device__ __forceinline__ void phase_attn_c(PP p, unsigned char* lds, int dry) {
;     ...
;         if (u < 1024) { const int sb = u >> 9; h = (u >> 6) & 7; qb = u & 63; start = TP + sb * 16384; len = 16384; }
;         else { const int v = u - 1024; const int sb = v >> 7; h = (v >> 4) & 7; qb = v & 15; start = sb * 4096; len = 4096; }
;         const size_t q0 = (size_t)(start + qb * 256);
;         att::attn_dense_body(QKV + q0 * 1536 + h * 128, QKV + (size_t)start * 1536 + 1024 + (h >> 2) * 128, QKV + (size_t)start * 1536 + 1280 + (h >> 2) * 128,
;                              O + q0 * 1024 + h * 128, len, (char*)lds, dry);
.LBB0_268:
	s_lshl_b32 s4, s29, 5
	s_cmpk_lt_i32 s29, 0x400
	s_movk_i32 s7, 0xc000
	s_cselect_b32 s5, 6, 4
	s_cselect_b32 s6, 63, 15
	s_cselect_b32 s7, s7, 0x7ffff000
	s_movk_i32 s37, 0x4000
	s_cselect_b32 s8, s37, 0xffff8000
	s_cselect_b32 s36, 0x100, 64
	s_lshr_b32 s12, s29, s5
	s_and_b32 s5, s6, s29
	s_and_b32 s4, s7, s4
	s_add_i32 s8, s4, s8
	s_lshl_b32 s4, s5, 8
	s_add_i32 s4, s8, s4
	s_and_b32 s6, s12, 7
	s_ashr_i32 s5, s4, 31
	s_mul_i32 s9, s4, 0xc00
	s_mul_hi_i32 s7, s4, 0xc00
	s_add_u32 s9, s30, s9
	s_addc_u32 s7, s31, s7
	s_lshl_b32 s35, s6, 7
	s_lshl_b32 s6, s6, 8
	s_add_u32 s10, s9, s6
	s_addc_u32 s11, s7, 0
	s_ashr_i32 s9, s8, 31
	s_mul_i32 s7, s8, 0xc00
	s_mul_hi_i32 s6, s8, 0xc00
	s_add_u32 s7, s30, s7
	s_addc_u32 s13, s31, s6
	s_lshl_b32 s6, s12, 6
	s_and_b32 s39, s6, 0x100
	v_mov_b32_e32 v70, v182
	s_add_u32 s6, s7, s39
	s_addc_u32 s7, s13, 0
	v_ashrrev_i32_e32 v48, 4, v70
	v_lshlrev_b32_e32 v18, 3, v70
	v_and_b32_e32 v71, 0x78, v18
	s_waitcnt vmcnt(0)
	v_mad_i64_i32 v[0:1], s[12:13], v48, s71, 0
	v_add_u32_e32 v19, 32, v48
	v_or_b32_e32 v0, v0, v71
	v_lshl_add_u64 v[8:9], v[0:1], 1, s[6:7]
	v_mad_i64_i32 v[4:5], s[12:13], v19, s71, 0
	global_load_dwordx4 v[0:3], v[8:9], off offset:2560
	v_or_b32_e32 v4, v4, v71
	v_lshl_add_u64 v[12:13], v[4:5], 1, s[6:7]
	global_load_dwordx4 v[4:7], v[12:13], off offset:2560
	s_nop 0
	global_load_dwordx4 v[8:11], v[8:9], off offset:2048
	s_nop 0
	global_load_dwordx4 v[12:15], v[12:13], off offset:2048
	v_ashrrev_i32_e32 v49, 1, v70
	s_movk_i32 s12, 0xffe0
	v_bfe_u32 v207, v70, 5, 1
	v_bfi_b32 v20, s12, v49, v70
	v_mov_b64_e32 v[16:17], s[10:11]
	v_mad_i64_i32 v[16:17], s[10:11], v20, s70, v[16:17]
	v_lshlrev_b32_e32 v96, 4, v207
	v_lshl_add_u64 v[16:17], v[16:17], 0, v[96:97]
	global_load_dwordx4 v[126:129], v[16:17], off
	global_load_dwordx4 v[122:125], v[16:17], off offset:32
	global_load_dwordx4 v[118:121], v[16:17], off offset:64
	global_load_dwordx4 v[114:117], v[16:17], off offset:96
	global_load_dwordx4 v[110:113], v[16:17], off offset:128
	global_load_dwordx4 v[106:109], v[16:17], off offset:160
	global_load_dwordx4 v[102:105], v[16:17], off offset:192
	global_load_dwordx4 v[98:101], v[16:17], off offset:224
	v_and_b32_e32 v21, 0xfffff0, v48
	v_lshlrev_b32_e32 v22, 1, v48
	v_lshrrev_b32_e32 v23, 1, v48
	v_and_b32_e32 v24, 3, v48
	v_and_or_b32 v21, v22, 8, v21
	v_and_or_b32 v22, v23, 4, v24
	v_and_b32_e32 v24, 0xfffff0, v19
	v_lshlrev_b32_e32 v26, 1, v19
	v_bfe_u32 v18, v18, 5, 2
	v_lshrrev_b32_e32 v21, 1, v21
	v_and_or_b32 v24, v26, 8, v24
	v_lshlrev_b32_e32 v23, 1, v71
	v_or_b32_e32 v21, v21, v18
	v_lshrrev_b32_e32 v24, 1, v24
	v_lshlrev_b32_e32 v22, 6, v22
	v_and_b32_e32 v27, 48, v23
	v_lshlrev_b32_e32 v21, 9, v21
	v_or_b32_e32 v18, v24, v18
	v_and_b32_e32 v20, 0x70, v70
	v_lshlrev_b32_e32 v25, 8, v48
	v_or3_b32 v216, v21, v22, v27
	v_lshlrev_b32_e32 v18, 9, v18
	v_bitop3_b32 v214, v23, v25, v20 bitop3:0xde
	v_and_b32_e32 v252, 0x80, v182
	v_lshlrev_b32_e32 v253, 4, v182
	v_and_b32_e32 v253, 0x80, v253
	v_xor_b32_e32 v214, v214, v252
	v_or3_b32 v217, v18, v22, v27
	v_bfe_u32 v250, v182, 7, 2
	v_lshlrev_b32_e32 v250, 11, v250
	v_bfe_u32 v251, v182, 4, 3
	v_lshl_or_b32 v250, v251, 6, v250
	v_bfe_u32 v251, v182, 2, 2
	v_lshl_or_b32 v250, v251, 9, v250
	v_and_b32_e32 v251, 3, v182
	v_lshl_or_b32 v216, v251, 4, v250
	v_add_u32_e32 v217, 0x2000, v216
	v_add_u32_e32 v72, 0, v216
	v_and_b32_e32 v208, 31, v70
	v_lshlrev_b32_e32 v50, 4, v70
	v_add_u32_e32 v73, 0, v217
	s_waitcnt vmcnt(0)
	s_add_i32 s10, 0, 0x18000
	v_and_b32_e32 v74, 63, v70
	s_cmp_lg_u32 0, -1
	s_mov_b32 s12, 0
	s_mov_b32 s13, s12
	v_and_b32_e32 v178, 0xffffffe0, v49
	s_waitcnt vmcnt(11)
	ds_write_b128 v72, v[0:3]
	s_waitcnt vmcnt(10)
	ds_write_b128 v73, v[4:7]
	v_add_u32_e32 v0, 0, v214
	s_waitcnt vmcnt(9)
	ds_write_b128 v0, v[8:11] offset:49152
	v_lshlrev_b32_e32 v0, 8, v19
	v_lshlrev_b32_e32 v8, 8, v208
	v_and_b32_e32 v9, 0x70, v50
	v_bitop3_b32 v219, v23, v0, v20 bitop3:0xde
	v_xor_b32_e32 v219, v219, v252
	v_bitop3_b32 v220, v96, v8, v9 bitop3:0xde
	v_xor_b32_e32 v220, v220, v253
	v_add_u32_e32 v0, 0, v219
	v_add_u32_e32 v4, 0, v220
	s_waitcnt vmcnt(8)
	ds_write_b128 v0, v[12:15] offset:49152
	s_waitcnt lgkmcnt(0)
	s_barrier
	ds_read_b128 v[0:3], v4 offset:49152
	ds_read_b128 v[4:7], v4 offset:57344
	s_waitcnt vmcnt(7) lgkmcnt(1)
	v_mfma_f32_32x32x16_bf16 v[16:31], v[0:3], v[126:129], 0
	v_or_b32_e32 v0, 32, v96
	v_bitop3_b32 v222, v0, v8, v9 bitop3:0xde
	v_xor_b32_e32 v222, v222, v253
	v_ashrrev_i32_e32 v49, 31, v48
	s_mov_b32 s14, s12
	s_mov_b32 s15, s12
	s_mov_b32 s16, s12
	s_mov_b32 s17, s12
	s_waitcnt lgkmcnt(0)
	v_mfma_f32_32x32x16_bf16 v[32:47], v[4:7], v[126:129], 0
	v_add_u32_e32 v4, 0, v222
	ds_read_b128 v[0:3], v4 offset:49152
	ds_read_b128 v[4:7], v4 offset:57344
	s_mov_b32 s18, s12
	s_mov_b32 s19, s12
	s_mov_b32 s20, s12
	s_mov_b32 s21, s12
	s_mov_b32 s22, s12
	s_waitcnt vmcnt(6) lgkmcnt(1)
	v_mfma_f32_32x32x16_bf16 v[16:31], v[0:3], v[122:125], v[16:31]
	v_or_b32_e32 v0, 64, v96
	v_bitop3_b32 v221, v0, v8, v9 bitop3:0xde
	v_xor_b32_e32 v221, v221, v253
	s_mov_b32 s23, s12
	s_mov_b32 s24, s12
	s_mov_b32 s25, s12
	s_mov_b32 s26, s12
	s_mov_b32 s27, s12
	s_waitcnt lgkmcnt(0)
	v_mfma_f32_32x32x16_bf16 v[32:47], v[4:7], v[122:125], v[32:47]
	v_add_u32_e32 v4, 0, v221
	ds_read_b128 v[0:3], v4 offset:49152
	ds_read_b128 v[4:7], v4 offset:57344
	s_mov_b32 s38, 2
	v_mov_b32_e32 v210, 0
	s_waitcnt vmcnt(5) lgkmcnt(1)
	v_mfma_f32_32x32x16_bf16 v[16:31], v[0:3], v[118:121], v[16:31]
	v_or_b32_e32 v0, 0x60, v96
	v_bitop3_b32 v218, v0, v8, v9 bitop3:0xde
	v_xor_b32_e32 v218, v218, v253
	s_waitcnt lgkmcnt(0)
; #define SLOAD(i, k0) do { sv0[i] = *(const bf16x8*)(&Vh[(long)((k0) + sr) * LDK + sc]); sv1[i] = *(const bf16x8*)(&Vh[(long)((k0) + 32 + sr) * LDK + sc]); \
;     sk0[i] = *(const bf16x8*)(&Kh[(long)((k0) + sr) * LDK + sc]); sk1[i] = *(const bf16x8*)(&Kh[(long)((k0) + 32 + sr) * LDK + sc]); } while (0)
; #define SWRITE(off, i) do { *(bf16x8*)((char*)V_lds + (off) + vst0) = sv0[i];          \
;     *(bf16x8*)((char*)V_lds + (off) + vst1) = sv1[i]; int kc = sc * 2;               \
;     *(bf16x8*)((char*)K_lds + (off) + KSWZ(sr, kc)) = sk0[i];                       \
;     *(bf16x8*)((char*)K_lds + (off) + KSWZ(32 + sr, kc)) = sk1[i]; } while (0)
; #define SWAIT() asm volatile("s_waitcnt vmcnt(4)" ::: "memory")
; __device__ __forceinline__ void partialSM(f32x16& p0, f32x16& p1, float& m_reg, float& mn, float& alpha) {
;     constexpr float C = SCALE * 1.4426950408889634f;
;     float pmax = p0[0];
; #pragma unroll
;     for (int r = 1; r < 16; ++r) pmax = fmaxf(pmax, p0[r]);
; #pragma unroll
;     for (int r = 0; r < 16; ++r) pmax = fmaxf(pmax, p1[r]);
;     { auto rr = __builtin_amdgcn_permlane32_swap(__float_as_uint(pmax), __float_as_uint(pmax), false, false);
;       pmax = fmaxf(__uint_as_float(rr[0]), __uint_as_float(rr[1])); }
;     if (__builtin_expect(__all(pmax - m_reg <= THR / SCALE), 1)) { mn = m_reg; alpha = 1.f; }
;     else { mn = fmaxf(m_reg, pmax); alpha = __builtin_amdgcn_exp2f((m_reg - mn) * C); m_reg = mn; }
; __device__ __forceinline__ void attn_dense_body(const bf16_t* __restrict__ Qb, const bf16_t* __restrict__ Kh, const bf16_t* __restrict__ Vh,
;                                                 bf16_t* __restrict__ Ob, int seq, char* lds, int dry) {
;     ...
;     SLOAD(0, 0); asm volatile("s_waitcnt vmcnt(0)" ::: "memory"); SWRITE(0, 0); __syncthreads();
;     qkt(pA0, pA1, K_lds, qr, r32, hi); partialSM(pA0, pA1, m_reg, mnA, alA);
;     SLOAD(1, KVBLK); if (2 < NT) SLOAD(0, 2 * KVBLK);
;     SWAIT(); SWRITE((int)SHM_K, 1); __syncthreads();
	v_mfma_f32_32x32x16_bf16 v[32:47], v[4:7], v[118:121], v[32:47]
	v_add_u32_e32 v4, 0, v218
	ds_read_b128 v[0:3], v4 offset:49152
	ds_read_b128 v[4:7], v4 offset:57344
	s_waitcnt vmcnt(4) lgkmcnt(1)
	v_mfma_f32_32x32x16_bf16 v[16:31], v[0:3], v[114:117], v[16:31]
	v_or_b32_e32 v0, 0x80, v96
	v_bitop3_b32 v215, v0, v8, v9 bitop3:0xde
	v_xor_b32_e32 v215, v215, v253
	s_waitcnt lgkmcnt(0)
	v_mfma_f32_32x32x16_bf16 v[32:47], v[4:7], v[114:117], v[32:47]
	v_add_u32_e32 v4, 0, v215
	ds_read_b128 v[0:3], v4 offset:49152
	ds_read_b128 v[4:7], v4 offset:57344
	s_waitcnt vmcnt(3) lgkmcnt(1)
	v_mfma_f32_32x32x16_bf16 v[16:31], v[0:3], v[110:113], v[16:31]
	v_or_b32_e32 v0, 0xa0, v96
	v_bitop3_b32 v213, v0, v8, v9 bitop3:0xde
	v_xor_b32_e32 v213, v213, v253
	s_waitcnt lgkmcnt(0)
	v_mfma_f32_32x32x16_bf16 v[32:47], v[4:7], v[110:113], v[32:47]
	v_add_u32_e32 v4, 0, v213
	ds_read_b128 v[0:3], v4 offset:49152
	v_and_b32_e32 v5, 0x3fffffc0, v70
	v_lshl_add_u32 v179, v5, 2, s10
	ds_read_b128 v[4:7], v4 offset:57344
	v_lshl_add_u32 v209, v208, 2, v179
	s_waitcnt vmcnt(2) lgkmcnt(1)
	v_mfma_f32_32x32x16_bf16 v[16:31], v[0:3], v[106:109], v[16:31]
	v_lshlrev_b32_e32 v0, 3, v74
	v_and_b32_e32 v1, 0xc0, v50
	v_and_or_b32 v10, v0, 24, v1
	v_lshlrev_b32_e32 v1, 1, v70
	v_and_b32_e32 v12, 0x100, v0
	v_add_u32_e32 v0, 64, v48
	v_and_b32_e32 v11, 32, v1
	s_waitcnt lgkmcnt(0)
	v_mfma_f32_32x32x16_bf16 v[32:47], v[4:7], v[106:109], v[32:47]
	v_or_b32_e32 v6, 0xc0, v96
	v_mad_i64_i32 v[0:1], s[10:11], v0, s71, 0
	v_add_u32_e32 v2, 0x60, v48
	v_or_b32_e32 v0, v0, v71
	v_mad_i64_i32 v[2:3], s[10:11], v2, s71, 0
	v_bitop3_b32 v223, v6, v8, v9 bitop3:0xde
	v_xor_b32_e32 v223, v223, v253
	v_lshl_add_u64 v[0:1], v[0:1], 1, s[6:7]
	v_or_b32_e32 v2, v2, v71
	v_add_u32_e32 v6, 0, v223
	global_load_dwordx4 v[50:53], v[0:1], off offset:2560
	global_load_dwordx4 v[58:61], v[0:1], off offset:2048
	v_lshl_add_u64 v[4:5], v[2:3], 1, s[6:7]
	ds_read_b128 v[0:3], v6 offset:49152
	s_waitcnt vmcnt(3) lgkmcnt(0)
	v_mfma_f32_32x32x16_bf16 v[16:31], v[0:3], v[102:105], v[16:31]
	v_or_b32_e32 v0, 0xe0, v96
	v_bitop3_b32 v224, v0, v8, v9 bitop3:0xde
	v_xor_b32_e32 v224, v224, v253
	global_load_dwordx4 v[54:57], v[4:5], off offset:2560
	global_load_dwordx4 v[62:65], v[4:5], off offset:2048
	v_or3_b32 v4, v10, v11, v12
	s_cselect_b32 s10, 0, 0
	v_add_u32_e32 v8, 0, v224
	v_add_u32_e32 v212, s10, v4
	ds_read_b128 v[4:7], v6 offset:57344
	ds_read_b128 v[0:3], v8 offset:49152
	ds_read_b128 v[66:69], v8 offset:57344
	s_waitcnt lgkmcnt(2)
	v_mfma_f32_32x32x16_bf16 v[32:47], v[4:7], v[102:105], v[32:47]
	s_waitcnt vmcnt(4) lgkmcnt(1)
	v_mfma_f32_32x32x16_bf16 v[16:31], v[0:3], v[98:101], v[16:31]
	v_mov_b64_e32 v[0:1], s[12:13]
	v_mov_b64_e32 v[2:3], s[14:15]
	v_mov_b64_e32 v[4:5], s[16:17]
	v_mov_b64_e32 v[6:7], s[18:19]
	v_mov_b64_e32 v[8:9], s[20:21]
	v_mov_b64_e32 v[10:11], s[22:23]
	v_mov_b64_e32 v[12:13], s[24:25]
	s_waitcnt lgkmcnt(0)
	v_mfma_f32_32x32x16_bf16 v[32:47], v[66:69], v[98:101], v[32:47]
	s_nop 2
	v_max_f32_e32 v66, v17, v17
	v_max_f32_e32 v67, v16, v16
	v_max_f32_e32 v66, v67, v66
	v_max3_f32 v66, v66, v18, v19
	v_max3_f32 v66, v66, v20, v21
	v_max3_f32 v66, v66, v22, v23
	v_max3_f32 v66, v66, v24, v25
	v_max3_f32 v66, v66, v26, v27
	v_max3_f32 v66, v66, v28, v29
	v_max3_f32 v66, v66, v30, v31
	v_max3_f32 v66, v66, v32, v33
	v_max3_f32 v66, v66, v34, v35
	v_max3_f32 v66, v66, v36, v37
	v_max3_f32 v66, v66, v38, v39
	v_max3_f32 v66, v66, v40, v41
	v_max3_f32 v66, v66, v42, v43
	v_max3_f32 v66, v66, v44, v45
	v_max3_f32 v75, v66, v46, v47
	v_mov_b32_e32 v66, v75
	s_nop 1
	v_permlane32_swap_b32_e32 v75, v66
	v_max_f32_e32 v76, v66, v66
	v_add_u32_e32 v66, 0xa0, v48
	v_mad_i64_i32 v[66:67], s[10:11], v66, s71, 0
	v_add_u32_e32 v68, 0x80, v48
	v_or_b32_e32 v66, v66, v71
	v_mad_i64_i32 v[68:69], s[10:11], v68, s71, 0
	v_lshl_add_u64 v[66:67], v[66:67], 1, s[6:7]
	v_or_b32_e32 v68, v68, v71
	v_lshl_add_u64 v[68:69], v[68:69], 1, s[6:7]
	global_load_dwordx4 v[130:133], v[66:67], off offset:2048
	global_load_dwordx4 v[142:145], v[66:67], off offset:2560
	global_load_dwordx4 v[138:141], v[68:69], off offset:2048
	global_load_dwordx4 v[134:137], v[68:69], off offset:2560
	v_max_f32_e32 v66, v75, v75
	v_max_f32_e32 v66, v66, v76
	v_add_f32_e32 v67, 0x7149f2ca, v66
	s_add_i32 s6, 0, 0x10000
	v_cmp_ge_f32_e32 vcc, s72, v67
	s_waitcnt vmcnt(4)
	s_waitcnt vmcnt(7)
	ds_write_b128 v72, v[50:53] offset:16384
	s_waitcnt vmcnt(5)
	ds_write_b128 v73, v[54:57] offset:16384
	v_add_u32_e32 v50, s6, v214
	ds_write_b128 v50, v[58:61]
	v_add_u32_e32 v50, s6, v219
	s_cmp_eq_u64 vcc, exec
	s_waitcnt vmcnt(4)
; #define SBAR() __builtin_amdgcn_sched_barrier(0)
; #define SLOAD(i, k0) do { sv0[i] = *(const bf16x8*)(&Vh[(long)((k0) + sr) * LDK + sc]); sv1[i] = *(const bf16x8*)(&Vh[(long)((k0) + 32 + sr) * LDK + sc]); \
;     sk0[i] = *(const bf16x8*)(&Kh[(long)((k0) + sr) * LDK + sc]); sk1[i] = *(const bf16x8*)(&Kh[(long)((k0) + 32 + sr) * LDK + sc]); } while (0)
; __device__ __forceinline__ void partialSM(f32x16& p0, f32x16& p1, float& m_reg, float& mn, float& alpha) {
;     ...
;     float mnC = -mn * C;
; #pragma unroll
;     for (int r = 0; r < 16; ++r) p0[r] = fmaf(p0[r], C, mnC);
; #pragma unroll
;     for (int r = 0; r < 16; ++r) p1[r] = fmaf(p1[r], C, mnC);
; #pragma unroll
;     for (int r = 0; r < 16; ++r) p0[r] = __builtin_amdgcn_exp2f(p0[r]);
; __device__ __forceinline__ void attn_dense_body(const bf16_t* __restrict__ Qb, const bf16_t* __restrict__ Kh, const bf16_t* __restrict__ Vh,
;                                                 bf16_t* __restrict__ Ob, int seq, char* lds, int dry) {
;     ...
;     int oq = (int)SHM_K, ov = 0, ow = 2 * (int)SHM_K;
;     for (int j = 1; j + 1 < NT; j += 2) {
;         SBAR(); qkt(pB0, pB1, (bf16_t*)((char*)K_lds + oq), qr, r32, hi);
;         finishSM(pA0, pA1, alA, l_reg, pa0, pa1, pa2, pa3); SBAR();
;         SLOAD(1, (j + 2) * KVBLK); SBAR();
;         pv_d0(o, vb0 + ov, pa0, pa1, pa2, pa3); partialSM(pB0, pB1, m_reg, mnB, alB);
	ds_write_b128 v50, v[62:65]
	v_max_f32_e32 v50, 0xf149f2ca, v66
	s_cselect_b64 vcc, -1, 0
	v_cndmask_b32_e32 v166, v50, v198, vcc
	v_sub_f32_e32 v51, 0xf149f2ca, v50
	v_mul_f32_e32 v50, 0xbe0293ee, v166
	v_fmamk_f32 v16, v16, 0x3e0293ee, v50
	v_mov_b32_e32 v163, v16
	v_fmamk_f32 v16, v17, 0x3e0293ee, v50
	v_mov_b32_e32 v177, v16
	v_fmamk_f32 v16, v18, 0x3e0293ee, v50
	v_mov_b32_e32 v164, v16
	v_fmamk_f32 v16, v19, 0x3e0293ee, v50
	v_exp_f32_e32 v229, v16
	v_fmamk_f32 v16, v20, 0x3e0293ee, v50
	v_mov_b32_e32 v176, v16
	v_fmamk_f32 v16, v21, 0x3e0293ee, v50
	v_exp_f32_e32 v230, v16
	v_fmamk_f32 v16, v22, 0x3e0293ee, v50
	v_mov_b32_e32 v165, v16
	v_fmamk_f32 v16, v23, 0x3e0293ee, v50
	v_mov_b32_e32 v175, v16
	v_fmamk_f32 v16, v24, 0x3e0293ee, v50
	v_mov_b32_e32 v171, v16
	v_fmamk_f32 v16, v25, 0x3e0293ee, v50
	v_mov_b32_e32 v173, v16
	v_fmamk_f32 v16, v26, 0x3e0293ee, v50
	v_mul_f32_e32 v51, 0x3e0293ee, v51
	v_mov_b32_e32 v172, v16
	v_fmamk_f32 v16, v27, 0x3e0293ee, v50
	v_exp_f32_e32 v51, v51
	v_mov_b32_e32 v174, v16
	v_fmamk_f32 v16, v28, 0x3e0293ee, v50
	v_mov_b32_e32 v167, v16
	v_fmamk_f32 v16, v29, 0x3e0293ee, v50
	v_mov_b32_e32 v169, v16
	v_fmamk_f32 v16, v30, 0x3e0293ee, v50
	v_mov_b64_e32 v[14:15], s[26:27]
	s_mov_b32 s20, 0x3e0293ee
	v_mov_b32_e32 v168, v16
	v_lshl_add_u64 v[16:17], v[48:49], 0, s[8:9]
	v_pk_fma_f32 v[146:147], v[46:47], s[20:21], v[50:51] op_sel_hi:[1,0,0]
	v_pk_fma_f32 v[148:149], v[44:45], s[20:21], v[50:51] op_sel_hi:[1,0,0]
	v_pk_fma_f32 v[150:151], v[42:43], s[20:21], v[50:51] op_sel_hi:[1,0,0]
	v_pk_fma_f32 v[152:153], v[40:41], s[20:21], v[50:51] op_sel_hi:[1,0,0]
	v_pk_fma_f32 v[154:155], v[38:39], s[20:21], v[50:51] op_sel_hi:[1,0,0]
	v_pk_fma_f32 v[156:157], v[36:37], s[20:21], v[50:51] op_sel_hi:[1,0,0]
	v_pk_fma_f32 v[158:159], v[34:35], s[20:21], v[50:51] op_sel_hi:[1,0,0]
	v_pk_fma_f32 v[160:161], v[32:33], s[20:21], v[50:51] op_sel_hi:[1,0,0]
	v_fmac_f32_e32 v50, 0x3e0293ee, v31
	v_mad_u64_u32 v[18:19], s[8:9], v16, s70, 0
	v_and_b32_e32 v16, 15, v70
	v_mov_b32_e32 v170, v50
	v_lshlrev_b32_e32 v16, 4, v16
	v_mad_i32_i24 v17, v17, s70, v19
	v_or3_b32 v16, v18, s39, v16
	v_cndmask_b32_e64 v225, v51, 1.0, vcc
	v_lshl_add_u64 v[180:181], s[2:3], 0, v[16:17]
	v_mov_b64_e32 v[62:63], v[14:15]
	v_mov_b64_e32 v[46:47], v[14:15]
	v_mov_b64_e32 v[30:31], v[14:15]
	v_cmp_gt_u32_e64 s[6:7], 32, v74
	s_mov_b32 s8, 0x8000
	v_mov_b64_e32 v[60:61], v[12:13]
	v_mov_b64_e32 v[58:59], v[10:11]
	v_mov_b64_e32 v[56:57], v[8:9]
	v_mov_b64_e32 v[54:55], v[6:7]
	v_mov_b64_e32 v[52:53], v[4:5]
	v_mov_b64_e32 v[50:51], v[2:3]
	v_mov_b64_e32 v[48:49], v[0:1]
	v_mov_b64_e32 v[44:45], v[12:13]
	v_mov_b64_e32 v[42:43], v[10:11]
	v_mov_b64_e32 v[40:41], v[8:9]
	v_mov_b64_e32 v[38:39], v[6:7]
	v_mov_b64_e32 v[36:37], v[4:5]
	v_mov_b64_e32 v[34:35], v[2:3]
	v_mov_b64_e32 v[32:33], v[0:1]
	v_mov_b64_e32 v[28:29], v[12:13]
	v_mov_b64_e32 v[26:27], v[10:11]
	v_mov_b64_e32 v[24:25], v[8:9]
	v_mov_b64_e32 v[22:23], v[6:7]
	v_mov_b64_e32 v[20:21], v[4:5]
	v_mov_b64_e32 v[18:19], v[2:3]
	v_mov_b64_e32 v[16:17], v[0:1]
	v_exp_f32_e32 v146, v146
	v_exp_f32_e32 v147, v147
	v_exp_f32_e32 v148, v148
	v_exp_f32_e32 v149, v149
	v_exp_f32_e32 v150, v150
	v_exp_f32_e32 v151, v151
	v_exp_f32_e32 v152, v152
	v_exp_f32_e32 v153, v153
	v_exp_f32_e32 v154, v154
	v_exp_f32_e32 v155, v155
	v_exp_f32_e32 v156, v156
	v_exp_f32_e32 v157, v157
	v_exp_f32_e32 v158, v158
	v_exp_f32_e32 v159, v159
	v_exp_f32_e32 v160, v160
	v_exp_f32_e32 v161, v161
	s_waitcnt lgkmcnt(0)
	s_barrier
	v_add_u32_e32 v220, 0x4000, v220
	v_add_u32_e32 v222, 0x4000, v222
	v_add_u32_e32 v221, 0x4000, v221
	v_add_u32_e32 v218, 0x4000, v218
	v_add_u32_e32 v215, 0x4000, v215
	v_add_u32_e32 v213, 0x4000, v213
	v_add_u32_e32 v223, 0x4000, v223
	v_add_u32_e32 v224, 0x4000, v224
	v_add_u32_e32 v219, 0x4000, v214
.LBB0_269:
	s_mov_b32 s13, s12
	s_mov_b32 s12, s8
	s_add_i32 s8, s37, 0
	ds_read_b128 v[64:67], v220 offset:49152
	ds_read_b128 v[68:71], v220 offset:57344
	ds_read_b128 v[232:235], v222 offset:49152
	ds_read_b128 v[236:239], v222 offset:57344
	ds_read_b128 v[240:243], v221 offset:49152
	ds_read_b128 v[244:247], v221 offset:57344
	s_waitcnt lgkmcnt(5)
	v_mfma_f32_32x32x16_bf16 v[80:95], v[64:67], v[126:129], 0
	v_exp_f32_e32 v163, v163
	v_exp_f32_e32 v177, v177
	v_exp_f32_e32 v164, v164
	v_exp_f32_e32 v176, v176
	s_waitcnt lgkmcnt(4)
	v_mfma_f32_32x32x16_bf16 v[64:79], v[68:71], v[126:129], 0
	v_exp_f32_e32 v165, v165
	v_exp_f32_e32 v175, v175
	v_exp_f32_e32 v171, v171
	v_exp_f32_e32 v173, v173
	s_waitcnt lgkmcnt(3)
	v_mfma_f32_32x32x16_bf16 v[80:95], v[232:235], v[122:125], v[80:95]
	v_exp_f32_e32 v172, v172
	v_exp_f32_e32 v174, v174
	v_exp_f32_e32 v167, v167
	v_exp_f32_e32 v169, v169
	s_waitcnt lgkmcnt(2)
	v_mfma_f32_32x32x16_bf16 v[64:79], v[236:239], v[122:125], v[64:79]
	ds_read_b128 v[232:235], v218 offset:49152
	ds_read_b128 v[236:239], v218 offset:57344
	v_exp_f32_e32 v168, v168
	v_exp_f32_e32 v170, v170
	v_add_f32_e32 v162, 0, v163
	v_add_f32_e32 v162, v177, v162
	s_waitcnt lgkmcnt(3)
	v_mfma_f32_32x32x16_bf16 v[80:95], v[240:243], v[118:121], v[80:95]
	v_add_f32_e32 v162, v164, v162
	v_add_f32_e32 v162, v229, v162
	v_add_f32_e32 v162, v176, v162
	v_add_f32_e32 v162, v230, v162
	s_waitcnt lgkmcnt(2)
	v_mfma_f32_32x32x16_bf16 v[64:79], v[244:247], v[118:121], v[64:79]
	ds_read_b128 v[240:243], v215 offset:49152
	ds_read_b128 v[244:247], v215 offset:57344
	v_add_f32_e32 v162, v165, v162
	v_add_f32_e32 v162, v175, v162
	v_add_f32_e32 v162, v171, v162
	v_add_f32_e32 v162, v173, v162
	s_waitcnt lgkmcnt(3)
; #define SBAR() __builtin_amdgcn_sched_barrier(0)
; #define SLOAD(i, k0) do { sv0[i] = *(const bf16x8*)(&Vh[(long)((k0) + sr) * LDK + sc]); sv1[i] = *(const bf16x8*)(&Vh[(long)((k0) + 32 + sr) * LDK + sc]); \
;     sk0[i] = *(const bf16x8*)(&Kh[(long)((k0) + sr) * LDK + sc]); sk1[i] = *(const bf16x8*)(&Kh[(long)((k0) + 32 + sr) * LDK + sc]); } while (0)
; #define SWRITE(off, i) do { *(bf16x8*)((char*)V_lds + (off) + vst0) = sv0[i];          \
;     *(bf16x8*)((char*)V_lds + (off) + vst1) = sv1[i]; int kc = sc * 2;               \
;     *(bf16x8*)((char*)K_lds + (off) + KSWZ(sr, kc)) = sk0[i];                       \
;     *(bf16x8*)((char*)K_lds + (off) + KSWZ(32 + sr, kc)) = sk1[i]; } while (0)
; #define SWAIT() asm volatile("s_waitcnt vmcnt(4)" ::: "memory")
; #define RESC(a) do { if (__any((a) < 1.f)) { if (hi == 0) al_l[r32] = (a); asm volatile("s_waitcnt lgkmcnt(0)" ::: "memory"); \
;     _Pragma("unroll") for (int d = 0; d < 4; ++d) _Pragma("unroll") for (int r = 0; r < 16; ++r) o[d][r] *= al_l[crow(r, hi)]; } } while (0)
; __device__ __forceinline__ void attn_dense_body(const bf16_t* __restrict__ Qb, const bf16_t* __restrict__ Kh, const bf16_t* __restrict__ Vh,
;                                                 bf16_t* __restrict__ Ob, int seq, char* lds, int dry) {
;     ...
;     for (int j = 1; j + 1 < NT; j += 2) {
;         SBAR(); qkt(pB0, pB1, (bf16_t*)((char*)K_lds + oq), qr, r32, hi);
;         finishSM(pA0, pA1, alA, l_reg, pa0, pa1, pa2, pa3); SBAR();
;         SLOAD(1, (j + 2) * KVBLK); SBAR();
;         pv_d0(o, vb0 + ov, pa0, pa1, pa2, pa3); partialSM(pB0, pB1, m_reg, mnB, alB);
;         SWAIT(); SWRITE(ow, 0);
;         RESC(alB); __syncthreads();
	v_mfma_f32_32x32x16_bf16 v[80:95], v[232:235], v[114:117], v[80:95]
	v_add_f32_e32 v162, v172, v162
	v_add_f32_e32 v162, v174, v162
	v_add_f32_e32 v162, v167, v162
	v_add_f32_e32 v162, v169, v162
	s_waitcnt lgkmcnt(2)
	v_mfma_f32_32x32x16_bf16 v[64:79], v[236:239], v[114:117], v[64:79]
	ds_read_b128 v[232:235], v213 offset:49152
	ds_read_b128 v[236:239], v213 offset:57344
	v_add_f32_e32 v162, v168, v162
	v_add_f32_e32 v162, v170, v162
	v_add_f32_e32 v162, v160, v162
	v_add_f32_e32 v162, v161, v162
	s_waitcnt lgkmcnt(3)
	v_mfma_f32_32x32x16_bf16 v[80:95], v[240:243], v[110:113], v[80:95]
	v_add_f32_e32 v162, v158, v162
	v_add_f32_e32 v162, v159, v162
	v_add_f32_e32 v162, v156, v162
	v_add_f32_e32 v162, v157, v162
	s_waitcnt lgkmcnt(2)
	v_mfma_f32_32x32x16_bf16 v[64:79], v[244:247], v[110:113], v[64:79]
	ds_read_b128 v[240:243], v223 offset:49152
	ds_read_b128 v[244:247], v223 offset:57344
	v_add_f32_e32 v162, v154, v162
	v_add_f32_e32 v162, v155, v162
	v_add_f32_e32 v162, v152, v162
	v_add_f32_e32 v162, v153, v162
	s_waitcnt lgkmcnt(3)
	v_mfma_f32_32x32x16_bf16 v[80:95], v[232:235], v[106:109], v[80:95]
	v_add_f32_e32 v162, v150, v162
	v_add_f32_e32 v162, v151, v162
	v_add_f32_e32 v162, v148, v162
	v_add_f32_e32 v162, v149, v162
	s_waitcnt lgkmcnt(2)
	v_mfma_f32_32x32x16_bf16 v[64:79], v[236:239], v[106:109], v[64:79]
	ds_read_b128 v[232:235], v224 offset:49152
	ds_read_b128 v[236:239], v224 offset:57344
	v_add_f32_e32 v162, v146, v162
	v_add_f32_e32 v226, v147, v162
	v_mov_b32_e32 v227, v226
	v_cvt_pk_bf16_f32 v162, v163, v177
	s_waitcnt lgkmcnt(3)
	v_mfma_f32_32x32x16_bf16 v[80:95], v[240:243], v[102:105], v[80:95]
	v_cvt_pk_bf16_f32 v163, v164, v229
	v_cvt_pk_bf16_f32 v164, v176, v230
	v_cvt_pk_bf16_f32 v165, v165, v175
	v_cvt_pk_bf16_f32 v228, v171, v173
	s_waitcnt lgkmcnt(2)
	v_mfma_f32_32x32x16_bf16 v[64:79], v[244:247], v[102:105], v[64:79]
	v_cvt_pk_bf16_f32 v229, v172, v174
	v_cvt_pk_bf16_f32 v230, v167, v169
	v_permlane32_swap_b32_e32 v226, v227
	v_cvt_pk_bf16_f32 v231, v168, v170
	s_waitcnt lgkmcnt(1)
	v_mfma_f32_32x32x16_bf16 v[80:95], v[232:235], v[98:101], v[80:95]
	v_cvt_pk_bf16_f32 v168, v160, v161
	v_cvt_pk_bf16_f32 v169, v158, v159
	v_cvt_pk_bf16_f32 v170, v156, v157
	v_cvt_pk_bf16_f32 v171, v154, v155
	s_waitcnt lgkmcnt(0)
	v_mfma_f32_32x32x16_bf16 v[64:79], v[236:239], v[98:101], v[64:79]
	v_cvt_pk_bf16_f32 v172, v152, v153
	v_cvt_pk_bf16_f32 v173, v150, v151
	v_cvt_pk_bf16_f32 v174, v148, v149
	v_cvt_pk_bf16_f32 v175, v146, v147
	s_mov_b32 s8, 0xfffb8000
	v_add_co_u32_e32 v150, vcc, s8, v180
	s_mov_b32 s8, 0xfffd0000
	s_nop 0
	v_addc_co_u32_e32 v151, vcc, -1, v181, vcc
	v_add_co_u32_e32 v154, vcc, s8, v180
	s_nop 1
	v_addc_co_u32_e32 v155, vcc, -1, v181, vcc
	global_load_dwordx4 v[146:149], v[150:151], off
	s_nop 0
	global_load_dwordx4 v[150:153], v[150:151], off offset:-512
	s_nop 0
	global_load_dwordx4 v[158:161], v[154:155], off
	s_nop 0
	global_load_dwordx4 v[154:157], v[154:155], off offset:-512
	v_add_u32_e32 v211, s13, v212
	ds_read_b64_tr_b16 v[232:233], v211 offset:0x0
	ds_read_b64_tr_b16 v[234:235], v211 offset:0x800
	ds_read_b64_tr_b16 v[236:237], v211 offset:0x1000
	ds_read_b64_tr_b16 v[238:239], v211 offset:0x1800
	ds_read_b64_tr_b16 v[240:241], v211 offset:0x2000
	ds_read_b64_tr_b16 v[242:243], v211 offset:0x2800
	ds_read_b64_tr_b16 v[244:245], v211 offset:0x3000
	ds_read_b64_tr_b16 v[246:247], v211 offset:0x3800
	s_waitcnt lgkmcnt(0)
	s_nop 0
	v_mfma_f32_32x32x16_bf16 v[0:15], v[162:165], v[232:235], v[0:15]
	ds_read_b64_tr_b16 v[232:233], v211 offset:0x200
	ds_read_b64_tr_b16 v[234:235], v211 offset:0xa00
	s_add_i32 s14, s12, 0
	s_waitcnt vmcnt(4)
	v_add_u32_e32 v253, s14, v216
	ds_write_b128 v253, v[134:137]
	v_max_f32_e32 v248, v80, v81
	v_max3_f32 v248, v248, v82, v83
	v_max3_f32 v248, v248, v84, v85
	v_max3_f32 v248, v248, v86, v87
	v_max3_f32 v248, v248, v88, v89
	v_mfma_f32_32x32x16_bf16 v[0:15], v[228:231], v[236:239], v[0:15]
	ds_read_b64_tr_b16 v[236:237], v211 offset:0x1200
	ds_read_b64_tr_b16 v[238:239], v211 offset:0x1a00
	ds_write_b128 v253, v[142:145] offset:8192
	v_max3_f32 v248, v248, v90, v91
	v_max3_f32 v248, v248, v92, v93
	v_max3_f32 v248, v248, v94, v95
	v_max3_f32 v248, v248, v64, v65
	v_mfma_f32_32x32x16_bf16 v[0:15], v[168:171], v[240:243], v[0:15]
	ds_read_b64_tr_b16 v[240:241], v211 offset:0x2200
	ds_read_b64_tr_b16 v[242:243], v211 offset:0x2a00
	ds_write_b128 v214, v[138:141] offset:49152
	v_max3_f32 v248, v248, v66, v67
	v_max3_f32 v248, v248, v68, v69
	v_max3_f32 v248, v248, v70, v71
	v_max3_f32 v248, v248, v72, v73
	v_mfma_f32_32x32x16_bf16 v[0:15], v[172:175], v[244:247], v[0:15]
	ds_read_b64_tr_b16 v[244:245], v211 offset:0x3200
	ds_read_b64_tr_b16 v[246:247], v211 offset:0x3a00
	ds_write_b128 v214, v[130:133] offset:57344
	v_max3_f32 v248, v248, v74, v75
	v_max3_f32 v248, v248, v76, v77
	v_max3_f32 v248, v248, v78, v79
	v_mov_b32_e32 v249, v248
	s_waitcnt lgkmcnt(0)
	v_mfma_f32_32x32x16_bf16 v[48:63], v[162:165], v[232:235], v[48:63]
	ds_read_b64_tr_b16 v[232:233], v211 offset:0x400
	ds_read_b64_tr_b16 v[234:235], v211 offset:0xc00
	v_permlane32_swap_b32_e32 v248, v249
	v_max_f32_e32 v248, v248, v249
	v_sub_f32_e32 v249, v248, v166
	v_cmp_ge_f32_e32 vcc, s72, v249
	v_mfma_f32_32x32x16_bf16 v[48:63], v[228:231], v[236:239], v[48:63]
	ds_read_b64_tr_b16 v[236:237], v211 offset:0x1400
	ds_read_b64_tr_b16 v[238:239], v211 offset:0x1c00
	v_mfma_f32_32x32x16_bf16 v[48:63], v[168:171], v[240:243], v[48:63]
	ds_read_b64_tr_b16 v[240:241], v211 offset:0x2400
	ds_read_b64_tr_b16 v[242:243], v211 offset:0x2c00
	s_cmp_eq_u64 vcc, exec
	s_cbranch_scc0 .Lmy_rare_h1
	v_mov_b32_e32 v167, 1.0
	s_mov_b64 s[8:9], 0
	v_mov_b32_e32 v176, v166
	v_mul_f32_e32 v177, 0xbe0293ee, v166
; #define SWRITE(off, i) do { *(bf16x8*)((char*)V_lds + (off) + vst0) = sv0[i];          \
;     *(bf16x8*)((char*)V_lds + (off) + vst1) = sv1[i]; int kc = sc * 2;               \
;     *(bf16x8*)((char*)K_lds + (off) + KSWZ(sr, kc)) = sk0[i];                       \
;     *(bf16x8*)((char*)K_lds + (off) + KSWZ(32 + sr, kc)) = sk1[i]; } while (0)
; #define SWAIT() asm volatile("s_waitcnt vmcnt(4)" ::: "memory")
; #define RESC(a) do { if (__any((a) < 1.f)) { if (hi == 0) al_l[r32] = (a); asm volatile("s_waitcnt lgkmcnt(0)" ::: "memory"); \
;     _Pragma("unroll") for (int d = 0; d < 4; ++d) _Pragma("unroll") for (int r = 0; r < 16; ++r) o[d][r] *= al_l[crow(r, hi)]; } } while (0)
; __device__ __forceinline__ void attn_dense_body(const bf16_t* __restrict__ Qb, const bf16_t* __restrict__ Kh, const bf16_t* __restrict__ Vh,
;                                                 bf16_t* __restrict__ Ob, int seq, char* lds, int dry) {
;     ...
;         pv_d0(o, vb0 + ov, pa0, pa1, pa2, pa3); partialSM(pB0, pB1, m_reg, mnB, alB);
;         SWAIT(); SWRITE(ow, 0);
;         RESC(alB); __syncthreads();
.Lmy_back_h1:
	v_mfma_f32_32x32x16_bf16 v[48:63], v[172:175], v[244:247], v[48:63]
	ds_read_b64_tr_b16 v[244:245], v211 offset:0x3400
	ds_read_b64_tr_b16 v[246:247], v211 offset:0x3c00
	s_waitcnt lgkmcnt(0)
	v_mfma_f32_32x32x16_bf16 v[32:47], v[162:165], v[232:235], v[32:47]
	ds_read_b64_tr_b16 v[232:233], v211 offset:0x600
	ds_read_b64_tr_b16 v[234:235], v211 offset:0xe00
	v_fmamk_f32 v250, v92, 0x3e0293ee, v177
	v_fmamk_f32 v251, v93, 0x3e0293ee, v177
	v_fmamk_f32 v252, v94, 0x3e0293ee, v177
	v_fmamk_f32 v253, v95, 0x3e0293ee, v177
	v_mfma_f32_32x32x16_bf16 v[32:47], v[228:231], v[236:239], v[32:47]
	ds_read_b64_tr_b16 v[236:237], v211 offset:0x1600
	ds_read_b64_tr_b16 v[238:239], v211 offset:0x1e00
	v_fmamk_f32 v248, v90, 0x3e0293ee, v177
	v_fmamk_f32 v249, v91, 0x3e0293ee, v177
	v_mfma_f32_32x32x16_bf16 v[32:47], v[168:171], v[240:243], v[32:47]
	ds_read_b64_tr_b16 v[240:241], v211 offset:0x2600
	ds_read_b64_tr_b16 v[242:243], v211 offset:0x2e00
	v_exp_f32_e32 v250, v250
	v_exp_f32_e32 v251, v251
	v_exp_f32_e32 v252, v252
	v_mfma_f32_32x32x16_bf16 v[32:47], v[172:175], v[244:247], v[32:47]
	ds_read_b64_tr_b16 v[244:245], v211 offset:0x3600
	ds_read_b64_tr_b16 v[246:247], v211 offset:0x3e00
	v_exp_f32_e32 v253, v253
	v_exp_f32_e32 v248, v248
	v_exp_f32_e32 v249, v249
	s_waitcnt lgkmcnt(0)
	v_mfma_f32_32x32x16_bf16 v[16:31], v[162:165], v[232:235], v[16:31]
	v_fmamk_f32 v232, v73, 0x3e0293ee, v177
	v_fmamk_f32 v233, v74, 0x3e0293ee, v177
	v_fmamk_f32 v234, v75, 0x3e0293ee, v177
	v_fmamk_f32 v235, v76, 0x3e0293ee, v177
	v_mfma_f32_32x32x16_bf16 v[16:31], v[228:231], v[236:239], v[16:31]
	v_fmamk_f32 v238, v80, 0x3e0293ee, v177
	v_fmamk_f32 v239, v81, 0x3e0293ee, v177
	v_fmamk_f32 v236, v77, 0x3e0293ee, v177
	v_fmamk_f32 v237, v78, 0x3e0293ee, v177
	v_fmamk_f32 v230, v71, 0x3e0293ee, v177
	v_fmamk_f32 v231, v72, 0x3e0293ee, v177
	v_mfma_f32_32x32x16_bf16 v[16:31], v[168:171], v[240:243], v[16:31]
	v_fmamk_f32 v240, v82, 0x3e0293ee, v177
	v_fmamk_f32 v241, v83, 0x3e0293ee, v177
	v_fmamk_f32 v242, v84, 0x3e0293ee, v177
	v_fmamk_f32 v243, v85, 0x3e0293ee, v177
	v_fmamk_f32 v170, v79, 0x3e0293ee, v177
	v_fmamk_f32 v171, v64, 0x3e0293ee, v177
	v_mfma_f32_32x32x16_bf16 v[16:31], v[172:175], v[244:247], v[16:31]
	v_fmamk_f32 v244, v86, 0x3e0293ee, v177
	v_fmamk_f32 v245, v87, 0x3e0293ee, v177
	v_fmamk_f32 v246, v88, 0x3e0293ee, v177
	v_fmamk_f32 v247, v89, 0x3e0293ee, v177
	v_fmamk_f32 v172, v65, 0x3e0293ee, v177
	v_fmamk_f32 v173, v66, 0x3e0293ee, v177
	v_fmamk_f32 v174, v67, 0x3e0293ee, v177
	v_fmamk_f32 v175, v68, 0x3e0293ee, v177
	v_mov_b32_e32 v228, v167
	s_and_b64 vcc, exec, s[8:9]
	s_cbranch_vccz .LBB0_273
	s_and_saveexec_b64 s[10:11], s[6:7]
	ds_write_b32 v209, v228 offset:128
	s_or_b64 exec, exec, s[10:11]
	s_waitcnt lgkmcnt(0)
	v_add_u32_e32 v163, v179, v96
	ds_read_b128 v[80:83], v163 offset:224
	ds_read_b128 v[84:87], v163 offset:192
	ds_read_b128 v[88:91], v163 offset:160
	ds_read_b128 v[92:95], v163 offset:128
	s_waitcnt lgkmcnt(3)
	v_pk_mul_f32 v[12:13], v[12:13], v[80:81]
	s_waitcnt lgkmcnt(2)
	v_pk_mul_f32 v[8:9], v[8:9], v[84:85]
	s_waitcnt lgkmcnt(1)
	v_pk_mul_f32 v[4:5], v[4:5], v[88:89]
	v_pk_mul_f32 v[14:15], v[14:15], v[82:83]
	v_pk_mul_f32 v[10:11], v[10:11], v[86:87]
	v_pk_mul_f32 v[6:7], v[6:7], v[90:91]
	s_waitcnt lgkmcnt(0)
	v_pk_mul_f32 v[2:3], v[2:3], v[94:95]
	v_pk_mul_f32 v[0:1], v[0:1], v[92:93]
	v_pk_mul_f32 v[60:61], v[60:61], v[80:81]
	v_pk_mul_f32 v[56:57], v[56:57], v[84:85]
	v_pk_mul_f32 v[52:53], v[52:53], v[88:89]
	v_pk_mul_f32 v[62:63], v[62:63], v[82:83]
	v_pk_mul_f32 v[58:59], v[58:59], v[86:87]
	v_pk_mul_f32 v[54:55], v[54:55], v[90:91]
	v_pk_mul_f32 v[50:51], v[50:51], v[94:95]
	v_pk_mul_f32 v[48:49], v[48:49], v[92:93]
	v_pk_mul_f32 v[44:45], v[44:45], v[80:81]
	v_pk_mul_f32 v[40:41], v[40:41], v[84:85]
	v_pk_mul_f32 v[36:37], v[36:37], v[88:89]
	v_pk_mul_f32 v[46:47], v[46:47], v[82:83]
	v_pk_mul_f32 v[42:43], v[42:43], v[86:87]
	v_pk_mul_f32 v[38:39], v[38:39], v[90:91]
	v_pk_mul_f32 v[34:35], v[34:35], v[94:95]
	v_pk_mul_f32 v[32:33], v[32:33], v[92:93]
	v_pk_mul_f32 v[28:29], v[28:29], v[80:81]
	v_pk_mul_f32 v[24:25], v[24:25], v[84:85]
	v_pk_mul_f32 v[20:21], v[20:21], v[88:89]
	v_pk_mul_f32 v[30:31], v[30:31], v[82:83]
	v_pk_mul_f32 v[26:27], v[26:27], v[86:87]
	v_pk_mul_f32 v[22:23], v[22:23], v[90:91]
	v_pk_mul_f32 v[18:19], v[18:19], v[94:95]
	v_pk_mul_f32 v[16:17], v[16:17], v[92:93]
; #define SBAR() __builtin_amdgcn_sched_barrier(0)
; #define SLOAD(i, k0) do { sv0[i] = *(const bf16x8*)(&Vh[(long)((k0) + sr) * LDK + sc]); sv1[i] = *(const bf16x8*)(&Vh[(long)((k0) + 32 + sr) * LDK + sc]); \
;     sk0[i] = *(const bf16x8*)(&Kh[(long)((k0) + sr) * LDK + sc]); sk1[i] = *(const bf16x8*)(&Kh[(long)((k0) + 32 + sr) * LDK + sc]); } while (0)
; __device__ __forceinline__ void attn_dense_body(const bf16_t* __restrict__ Qb, const bf16_t* __restrict__ Kh, const bf16_t* __restrict__ Vh,
;                                                 bf16_t* __restrict__ Ob, int seq, char* lds, int dry) {
;     ...
;         { const int t_ = ov; ov = oq; oq = ow; ow = t_; }
;         SBAR(); qkt(pA0, pA1, (bf16_t*)((char*)K_lds + oq), qr, r32, hi);
;         finishSM(pB0, pB1, alB, l_reg, pa0, pa1, pa2, pa3); SBAR();
;         if (j + 3 < NT) SLOAD(0, (j + 3) * KVBLK); SBAR();
.LBB0_273:
	v_mov_b32_e32 v229, v176
	v_fmamk_f32 v176, v69, 0x3e0293ee, v177
	v_fmac_f32_e32 v177, 0x3e0293ee, v70
	s_waitcnt lgkmcnt(0)
	s_barrier
	ds_read_b128 v[64:67], v220 offset:32768
	ds_read_b128 v[68:71], v220 offset:40960
	ds_read_b128 v[130:133], v222 offset:32768
	ds_read_b128 v[134:137], v222 offset:40960
	ds_read_b128 v[138:141], v221 offset:32768
	ds_read_b128 v[142:145], v221 offset:40960
	s_waitcnt lgkmcnt(5)
	v_mfma_f32_32x32x16_bf16 v[80:95], v[64:67], v[126:129], 0
	v_exp_f32_e32 v238, v238
	v_exp_f32_e32 v239, v239
	v_exp_f32_e32 v240, v240
	v_exp_f32_e32 v241, v241
	v_exp_f32_e32 v242, v242
	s_waitcnt lgkmcnt(4)
	v_mfma_f32_32x32x16_bf16 v[64:79], v[68:71], v[126:129], 0
	v_exp_f32_e32 v243, v243
	v_exp_f32_e32 v244, v244
	v_exp_f32_e32 v245, v245
	v_exp_f32_e32 v246, v246
	v_exp_f32_e32 v247, v247
	s_waitcnt lgkmcnt(3)
	v_mfma_f32_32x32x16_bf16 v[80:95], v[130:133], v[122:125], v[80:95]
	v_add_f32_e32 v162, 0, v238
	v_exp_f32_e32 v171, v171
	v_add_f32_e32 v162, v239, v162
	v_exp_f32_e32 v172, v172
	v_add_f32_e32 v162, v240, v162
	s_waitcnt lgkmcnt(2)
	v_mfma_f32_32x32x16_bf16 v[64:79], v[134:137], v[122:125], v[64:79]
	ds_read_b128 v[130:133], v218 offset:32768
	ds_read_b128 v[134:137], v218 offset:40960
	v_exp_f32_e32 v173, v173
	v_add_f32_e32 v162, v241, v162
	v_exp_f32_e32 v174, v174
	v_add_f32_e32 v162, v242, v162
	v_exp_f32_e32 v175, v175
	s_waitcnt lgkmcnt(3)
	v_mfma_f32_32x32x16_bf16 v[80:95], v[138:141], v[118:121], v[80:95]
	v_add_f32_e32 v162, v243, v162
	v_exp_f32_e32 v176, v176
	v_add_f32_e32 v162, v244, v162
	v_exp_f32_e32 v177, v177
	v_add_f32_e32 v162, v245, v162
	s_waitcnt lgkmcnt(2)
	v_mfma_f32_32x32x16_bf16 v[64:79], v[142:145], v[118:121], v[64:79]
	ds_read_b128 v[138:141], v215 offset:32768
	ds_read_b128 v[142:145], v215 offset:40960
	v_exp_f32_e32 v230, v230
	v_add_f32_e32 v162, v246, v162
	v_exp_f32_e32 v188, v231
	v_add_f32_e32 v162, v247, v162
	v_exp_f32_e32 v186, v232
	s_waitcnt lgkmcnt(3)
	v_mfma_f32_32x32x16_bf16 v[80:95], v[130:133], v[114:117], v[80:95]
	v_add_f32_e32 v162, v248, v162
	v_exp_f32_e32 v233, v233
	v_add_f32_e32 v162, v249, v162
	v_exp_f32_e32 v234, v234
	v_add_f32_e32 v162, v250, v162
	s_waitcnt lgkmcnt(2)
	v_mfma_f32_32x32x16_bf16 v[64:79], v[134:137], v[114:117], v[64:79]
	ds_read_b128 v[130:133], v213 offset:32768
	ds_read_b128 v[134:137], v213 offset:40960
	v_exp_f32_e32 v235, v235
	v_add_f32_e32 v162, v251, v162
	v_exp_f32_e32 v236, v236
	v_add_f32_e32 v162, v252, v162
	v_exp_f32_e32 v237, v237
	s_waitcnt lgkmcnt(3)
	v_mfma_f32_32x32x16_bf16 v[80:95], v[138:141], v[110:113], v[80:95]
	v_add_f32_e32 v162, v253, v162
	v_exp_f32_e32 v194, v170
	v_add_f32_e32 v162, v171, v162
	v_add_f32_e32 v162, v172, v162
	v_add_f32_e32 v162, v173, v162
	s_waitcnt lgkmcnt(2)
	v_mfma_f32_32x32x16_bf16 v[64:79], v[142:145], v[110:113], v[64:79]
	ds_read_b128 v[138:141], v223 offset:32768
	ds_read_b128 v[142:145], v223 offset:40960
	v_add_f32_e32 v162, v174, v162
	v_add_f32_e32 v162, v175, v162
	v_add_f32_e32 v162, v176, v162
	v_add_f32_e32 v162, v177, v162
	v_add_f32_e32 v162, v230, v162
	s_waitcnt lgkmcnt(3)
	v_mfma_f32_32x32x16_bf16 v[80:95], v[130:133], v[106:109], v[80:95]
	v_add_f32_e32 v162, v188, v162
	v_add_f32_e32 v162, v186, v162
	v_add_f32_e32 v162, v233, v162
	v_add_f32_e32 v162, v234, v162
	v_add_f32_e32 v162, v235, v162
	s_waitcnt lgkmcnt(2)
	v_mfma_f32_32x32x16_bf16 v[64:79], v[134:137], v[106:109], v[64:79]
	ds_read_b128 v[130:133], v224 offset:32768
	ds_read_b128 v[134:137], v224 offset:40960
	v_add_f32_e32 v162, v236, v162
	v_add_f32_e32 v162, v237, v162
	v_add_f32_e32 v231, v194, v162
	v_mov_b32_e32 v232, v231
	v_cvt_pk_bf16_f32 v162, v238, v239
	s_waitcnt lgkmcnt(3)
	v_mfma_f32_32x32x16_bf16 v[80:95], v[138:141], v[102:105], v[80:95]
	v_cvt_pk_bf16_f32 v163, v240, v241
	v_cvt_pk_bf16_f32 v164, v242, v243
	v_cvt_pk_bf16_f32 v165, v244, v245
	v_cvt_pk_bf16_f32 v166, v246, v247
	v_cvt_pk_bf16_f32 v167, v248, v249
	s_waitcnt lgkmcnt(2)
	v_mfma_f32_32x32x16_bf16 v[64:79], v[142:145], v[102:105], v[64:79]
	v_cvt_pk_bf16_f32 v168, v250, v251
	v_cvt_pk_bf16_f32 v169, v252, v253
	v_cvt_pk_bf16_f32 v170, v171, v172
	v_cvt_pk_bf16_f32 v171, v173, v174
	s_waitcnt lgkmcnt(1)
	v_mfma_f32_32x32x16_bf16 v[80:95], v[130:133], v[98:101], v[80:95]
	v_cvt_pk_bf16_f32 v172, v175, v176
	v_cvt_pk_bf16_f32 v173, v177, v230
	v_cvt_pk_bf16_f32 v174, v188, v186
	v_cvt_pk_bf16_f32 v175, v233, v234
	s_waitcnt lgkmcnt(0)
	v_mfma_f32_32x32x16_bf16 v[64:79], v[134:137], v[98:101], v[64:79]
	v_cvt_pk_bf16_f32 v176, v235, v236
	v_cvt_pk_bf16_f32 v177, v237, v194
	s_nop 1
	v_permlane32_swap_b32_e32 v231, v232
	s_add_i32 s38, s38, 2
	s_cmp_ge_u32 s38, s36
	s_cselect_b64 s[10:11], -1, 0
	s_and_b64 vcc, exec, s[10:11]
	s_cbranch_vccnz .LBB0_275
	v_add_co_u32_e32 v130, vcc, 0xfffe8000, v180
	s_nop 1
	v_addc_co_u32_e32 v131, vcc, -1, v181, vcc
	global_load_dwordx4 v[134:137], v[130:131], off
	global_load_dwordx4 v[138:141], v[130:131], off offset:-512
	global_load_dwordx4 v[142:145], v[180:181], off
	s_nop 0
	global_load_dwordx4 v[130:133], v[180:181], off offset:-512

; #define SWRITE(off, i) do { *(bf16x8*)((char*)V_lds + (off) + vst0) = sv0[i];          \
;     *(bf16x8*)((char*)V_lds + (off) + vst1) = sv1[i]; int kc = sc * 2;               \
;     *(bf16x8*)((char*)K_lds + (off) + KSWZ(sr, kc)) = sk0[i];                       \
;     *(bf16x8*)((char*)K_lds + (off) + KSWZ(32 + sr, kc)) = sk1[i]; } while (0)
; #define SWAIT() asm volatile("s_waitcnt vmcnt(4)" ::: "memory")
; #define RESC(a) do { if (__any((a) < 1.f)) { if (hi == 0) al_l[r32] = (a); asm volatile("s_waitcnt lgkmcnt(0)" ::: "memory"); \
;     _Pragma("unroll") for (int d = 0; d < 4; ++d) _Pragma("unroll") for (int r = 0; r < 16; ++r) o[d][r] *= al_l[crow(r, hi)]; } } while (0)
; __device__ __forceinline__ void partialSM(f32x16& p0, f32x16& p1, float& m_reg, float& mn, float& alpha) {
;     constexpr float C = SCALE * 1.4426950408889634f;
;     float pmax = p0[0];
; #pragma unroll
;     for (int r = 1; r < 16; ++r) pmax = fmaxf(pmax, p0[r]);
; #pragma unroll
;     for (int r = 0; r < 16; ++r) pmax = fmaxf(pmax, p1[r]);
;     { auto rr = __builtin_amdgcn_permlane32_swap(__float_as_uint(pmax), __float_as_uint(pmax), false, false);
;       pmax = fmaxf(__uint_as_float(rr[0]), __uint_as_float(rr[1])); }
;     if (__builtin_expect(__all(pmax - m_reg <= THR / SCALE), 1)) { mn = m_reg; alpha = 1.f; }
;     else { mn = fmaxf(m_reg, pmax); alpha = __builtin_amdgcn_exp2f((m_reg - mn) * C); m_reg = mn; }
; __device__ __forceinline__ void attn_dense_body(const bf16_t* __restrict__ Qb, const bf16_t* __restrict__ Kh, const bf16_t* __restrict__ Vh,
;                                                 bf16_t* __restrict__ Ob, int seq, char* lds, int dry) {
;     ...
;         pv_d0(o, vb0 + ov, pa0, pa1, pa2, pa3); partialSM(pA0, pA1, m_reg, mnA, alA);
;         SWAIT(); SWRITE(ow, 1);
;         RESC(alA); __syncthreads();
.Lmy_sw_join:
	v_add_u32_e32 v194, s16, v216
	ds_write_b128 v194, v[146:149]
	v_max_f32_e32 v250, v80, v81
	v_max3_f32 v250, v250, v82, v83
	v_max3_f32 v250, v250, v84, v85
	v_max3_f32 v250, v250, v86, v87
	v_max3_f32 v250, v250, v88, v89
	v_mfma_f32_32x32x16_bf16 v[0:15], v[166:169], v[238:241], v[0:15]
	ds_read_b64_tr_b16 v[238:239], v186 offset:0x1200
	ds_read_b64_tr_b16 v[240:241], v186 offset:0x1a00
	ds_write_b128 v194, v[158:161] offset:8192
	v_max3_f32 v250, v250, v90, v91
	v_max3_f32 v250, v250, v92, v93
	v_max3_f32 v250, v250, v94, v95
	v_max3_f32 v250, v250, v64, v65
	v_mfma_f32_32x32x16_bf16 v[0:15], v[170:173], v[242:245], v[0:15]
	ds_read_b64_tr_b16 v[242:243], v186 offset:0x2200
	ds_read_b64_tr_b16 v[244:245], v186 offset:0x2a00
	ds_write_b128 v219, v[150:153] offset:49152
	v_max3_f32 v250, v250, v66, v67
	v_max3_f32 v250, v250, v68, v69
	v_max3_f32 v250, v250, v70, v71
	v_max3_f32 v250, v250, v72, v73
	v_mfma_f32_32x32x16_bf16 v[0:15], v[174:177], v[246:249], v[0:15]
	ds_read_b64_tr_b16 v[246:247], v186 offset:0x3200
	ds_read_b64_tr_b16 v[248:249], v186 offset:0x3a00
	ds_write_b128 v219, v[154:157] offset:57344
	v_max3_f32 v250, v250, v74, v75
	v_max3_f32 v250, v250, v76, v77
	v_max3_f32 v250, v250, v78, v79
	v_mov_b32_e32 v251, v250
	s_waitcnt lgkmcnt(0)
	v_mfma_f32_32x32x16_bf16 v[48:63], v[162:165], v[234:237], v[48:63]
	ds_read_b64_tr_b16 v[234:235], v186 offset:0x400
	ds_read_b64_tr_b16 v[236:237], v186 offset:0xc00
	v_permlane32_swap_b32_e32 v250, v251
	v_max_f32_e32 v250, v250, v251
	v_sub_f32_e32 v251, v250, v229
	v_cmp_ge_f32_e32 vcc, s72, v251
	v_mfma_f32_32x32x16_bf16 v[48:63], v[166:169], v[238:241], v[48:63]
	ds_read_b64_tr_b16 v[238:239], v186 offset:0x1400
	ds_read_b64_tr_b16 v[240:241], v186 offset:0x1c00
	v_mfma_f32_32x32x16_bf16 v[48:63], v[170:173], v[242:245], v[48:63]
	ds_read_b64_tr_b16 v[242:243], v186 offset:0x2400
	ds_read_b64_tr_b16 v[244:245], v186 offset:0x2c00
	s_cmp_eq_u64 vcc, exec
	s_cbranch_scc0 .Lmy_rare_h2
	v_mov_b32_e32 v252, 1.0
	s_mov_b64 s[8:9], 0
	v_mov_b32_e32 v253, v229
	v_mul_f32_e32 v188, 0xbe0293ee, v229
.Lmy_back_h2:
	v_mfma_f32_32x32x16_bf16 v[48:63], v[174:177], v[246:249], v[48:63]
	ds_read_b64_tr_b16 v[246:247], v186 offset:0x3400
	ds_read_b64_tr_b16 v[248:249], v186 offset:0x3c00
	s_waitcnt lgkmcnt(0)
	v_mfma_f32_32x32x16_bf16 v[32:47], v[162:165], v[234:237], v[32:47]
	ds_read_b64_tr_b16 v[234:235], v186 offset:0x600
	ds_read_b64_tr_b16 v[236:237], v186 offset:0xe00
	v_fmamk_f32 v230, v85, 0x3e0293ee, v188
	v_fmamk_f32 v229, v83, 0x3e0293ee, v188
	v_fmamk_f32 v160, v64, 0x3e0293ee, v188
	v_fmamk_f32 v161, v65, 0x3e0293ee, v188
	v_fmamk_f32 v158, v66, 0x3e0293ee, v188
	v_mfma_f32_32x32x16_bf16 v[32:47], v[166:169], v[238:241], v[32:47]
	ds_read_b64_tr_b16 v[238:239], v186 offset:0x1600
	ds_read_b64_tr_b16 v[240:241], v186 offset:0x1e00
	v_fmamk_f32 v159, v67, 0x3e0293ee, v188
	v_fmamk_f32 v156, v68, 0x3e0293ee, v188
	v_fmamk_f32 v157, v69, 0x3e0293ee, v188
	v_fmamk_f32 v154, v70, 0x3e0293ee, v188
	v_fmamk_f32 v155, v71, 0x3e0293ee, v188
	v_exp_f32_e32 v230, v230
	v_exp_f32_e32 v229, v229
	v_mfma_f32_32x32x16_bf16 v[32:47], v[170:173], v[242:245], v[32:47]
	ds_read_b64_tr_b16 v[242:243], v186 offset:0x2600
	ds_read_b64_tr_b16 v[244:245], v186 offset:0x2e00
	v_fmamk_f32 v152, v72, 0x3e0293ee, v188
	v_fmamk_f32 v153, v73, 0x3e0293ee, v188
	v_fmamk_f32 v150, v74, 0x3e0293ee, v188
	v_fmamk_f32 v151, v75, 0x3e0293ee, v188
	v_fmamk_f32 v148, v76, 0x3e0293ee, v188
	v_exp_f32_e32 v160, v160
	v_exp_f32_e32 v161, v161
	v_mfma_f32_32x32x16_bf16 v[32:47], v[174:177], v[246:249], v[32:47]
	ds_read_b64_tr_b16 v[246:247], v186 offset:0x3600
	ds_read_b64_tr_b16 v[248:249], v186 offset:0x3e00
	v_fmamk_f32 v149, v77, 0x3e0293ee, v188
	v_fmamk_f32 v146, v78, 0x3e0293ee, v188
	v_fmamk_f32 v147, v79, 0x3e0293ee, v188
	v_exp_f32_e32 v158, v158
	v_exp_f32_e32 v159, v159
	v_exp_f32_e32 v156, v156
	s_waitcnt lgkmcnt(0)
	v_mfma_f32_32x32x16_bf16 v[16:31], v[162:165], v[234:237], v[16:31]
	v_fmamk_f32 v163, v80, 0x3e0293ee, v188
	v_fmamk_f32 v164, v82, 0x3e0293ee, v188
	v_fmamk_f32 v165, v86, 0x3e0293ee, v188
	v_exp_f32_e32 v157, v157
	v_exp_f32_e32 v154, v154
	v_exp_f32_e32 v155, v155
	v_mfma_f32_32x32x16_bf16 v[16:31], v[166:169], v[238:241], v[16:31]
	v_fmamk_f32 v167, v92, 0x3e0293ee, v188
	v_fmamk_f32 v169, v93, 0x3e0293ee, v188
	v_fmamk_f32 v168, v94, 0x3e0293ee, v188
	v_exp_f32_e32 v152, v152
	v_exp_f32_e32 v153, v153
	v_exp_f32_e32 v150, v150
	v_mfma_f32_32x32x16_bf16 v[16:31], v[170:173], v[242:245], v[16:31]
	v_fmamk_f32 v171, v88, 0x3e0293ee, v188
	v_fmamk_f32 v173, v89, 0x3e0293ee, v188
	v_fmamk_f32 v172, v90, 0x3e0293ee, v188
	v_fmamk_f32 v170, v95, 0x3e0293ee, v188
	v_exp_f32_e32 v151, v151
	v_exp_f32_e32 v148, v148
	v_exp_f32_e32 v149, v149
	v_mfma_f32_32x32x16_bf16 v[16:31], v[174:177], v[246:249], v[16:31]
	v_fmamk_f32 v177, v81, 0x3e0293ee, v188
	v_fmamk_f32 v176, v84, 0x3e0293ee, v188
	v_fmamk_f32 v175, v87, 0x3e0293ee, v188
	v_fmamk_f32 v174, v91, 0x3e0293ee, v188
	v_exp_f32_e32 v146, v146
	v_exp_f32_e32 v147, v147
	v_mov_b32_e32 v162, v252
	s_and_b64 vcc, exec, s[8:9]
	s_cbranch_vccz .LBB0_279
	s_and_saveexec_b64 s[14:15], s[6:7]
	ds_write_b32 v209, v162 offset:128
	s_or_b64 exec, exec, s[14:15]
	s_waitcnt lgkmcnt(0)
	v_add_u32_e32 v250, v179, v96
	ds_read_b128 v[80:83], v250 offset:224
	ds_read_b128 v[84:87], v250 offset:192
	ds_read_b128 v[88:91], v250 offset:160
	ds_read_b128 v[92:95], v250 offset:128
	s_waitcnt lgkmcnt(3)
	v_pk_mul_f32 v[12:13], v[12:13], v[80:81]
	s_waitcnt lgkmcnt(2)
	v_pk_mul_f32 v[8:9], v[8:9], v[84:85]
	s_waitcnt lgkmcnt(1)
	v_pk_mul_f32 v[4:5], v[4:5], v[88:89]
	v_pk_mul_f32 v[14:15], v[14:15], v[82:83]
	v_pk_mul_f32 v[10:11], v[10:11], v[86:87]
	v_pk_mul_f32 v[6:7], v[6:7], v[90:91]
	s_waitcnt lgkmcnt(0)
	v_pk_mul_f32 v[2:3], v[2:3], v[94:95]
	v_pk_mul_f32 v[0:1], v[0:1], v[92:93]
	v_pk_mul_f32 v[60:61], v[60:61], v[80:81]
	v_pk_mul_f32 v[56:57], v[56:57], v[84:85]
	v_pk_mul_f32 v[52:53], v[52:53], v[88:89]
	v_pk_mul_f32 v[62:63], v[62:63], v[82:83]
	v_pk_mul_f32 v[58:59], v[58:59], v[86:87]
	v_pk_mul_f32 v[54:55], v[54:55], v[90:91]
	v_pk_mul_f32 v[50:51], v[50:51], v[94:95]
	v_pk_mul_f32 v[48:49], v[48:49], v[92:93]
	v_pk_mul_f32 v[44:45], v[44:45], v[80:81]
	v_pk_mul_f32 v[40:41], v[40:41], v[84:85]
	v_pk_mul_f32 v[36:37], v[36:37], v[88:89]
	v_pk_mul_f32 v[46:47], v[46:47], v[82:83]
	v_pk_mul_f32 v[42:43], v[42:43], v[86:87]
	v_pk_mul_f32 v[38:39], v[38:39], v[90:91]
	v_pk_mul_f32 v[34:35], v[34:35], v[94:95]
	v_pk_mul_f32 v[32:33], v[32:33], v[92:93]
	v_pk_mul_f32 v[28:29], v[28:29], v[80:81]
	v_pk_mul_f32 v[24:25], v[24:25], v[84:85]
	v_pk_mul_f32 v[20:21], v[20:21], v[88:89]
	v_pk_mul_f32 v[30:31], v[30:31], v[82:83]
	v_pk_mul_f32 v[26:27], v[26:27], v[86:87]
	v_pk_mul_f32 v[22:23], v[22:23], v[90:91]
	v_pk_mul_f32 v[18:19], v[18:19], v[94:95]
	v_pk_mul_f32 v[16:17], v[16:17], v[92:93]

; #define SBAR() __builtin_amdgcn_sched_barrier(0)
; __device__ __forceinline__ void attn_dense_body(const bf16_t* __restrict__ Qb, const bf16_t* __restrict__ Kh, const bf16_t* __restrict__ Vh,
;                                                 bf16_t* __restrict__ Ob, int seq, char* lds, int dry) {
;     ...
;     SBAR(); qkt(pB0, pB1, (bf16_t*)((char*)K_lds + oq), qr, r32, hi);
;     finishSM(pA0, pA1, alA, l_reg, pa0, pa1, pa2, pa3); SBAR();
;     pv_d0(o, vb0 + ov, pa0, pa1, pa2, pa3); partialSM(pB0, pB1, m_reg, mnB, alB);
.Lmy_rare_h1:
	v_max_f32_e32 v248, v166, v248
	v_sub_f32_e32 v249, v166, v248
	v_mul_f32_e32 v249, 0x3e0293ee, v249
	v_exp_f32_e32 v249, v249
	s_nop 0
	v_mov_b32_e32 v167, v249
	s_mov_b64 s[8:9], -1
	v_mov_b32_e32 v176, v248
	v_mul_f32_e32 v177, 0xbe0293ee, v176
	s_branch .Lmy_back_h1
.Lmy_rare_h2:
	v_max_f32_e32 v250, v229, v250
	v_sub_f32_e32 v251, v229, v250
	v_mul_f32_e32 v251, 0x3e0293ee, v251
	v_exp_f32_e32 v251, v251
	s_nop 0
	v_mov_b32_e32 v252, v251
	s_mov_b64 s[8:9], -1
	v_mov_b32_e32 v253, v250
	v_mul_f32_e32 v188, 0xbe0293ee, v253
	s_branch .Lmy_back_h2
.LBB0_281:
	v_exp_f32_e32 v163, v163
	v_exp_f32_e32 v177, v177
	v_exp_f32_e32 v164, v164
	v_exp_f32_e32 v176, v176
	v_exp_f32_e32 v165, v165
	v_exp_f32_e32 v175, v175
	v_exp_f32_e32 v171, v171
	v_exp_f32_e32 v173, v173
	v_exp_f32_e32 v172, v172
	v_exp_f32_e32 v174, v174
	v_exp_f32_e32 v167, v167
	v_exp_f32_e32 v169, v169
	v_exp_f32_e32 v168, v168
	v_exp_f32_e32 v170, v170
	v_mov_b32_e32 v68, v220
	ds_read_b128 v[64:67], v68 offset:49152
	ds_read_b128 v[68:71], v68 offset:57344
	v_mov_b32_e32 v130, v222
	s_waitcnt lgkmcnt(1)
	v_mfma_f32_32x32x16_bf16 v[80:95], v[64:67], v[126:129], 0
	s_waitcnt lgkmcnt(0)
	v_mfma_f32_32x32x16_bf16 v[64:79], v[68:71], v[126:129], 0
	ds_read_b128 v[126:129], v130 offset:49152
	ds_read_b128 v[130:133], v130 offset:57344
	s_waitcnt lgkmcnt(1)
	v_mfma_f32_32x32x16_bf16 v[80:95], v[126:129], v[122:125], v[80:95]
	v_mov_b32_e32 v126, v221
	s_waitcnt lgkmcnt(0)
	v_mfma_f32_32x32x16_bf16 v[64:79], v[130:133], v[122:125], v[64:79]
	ds_read_b128 v[122:125], v126 offset:49152
	ds_read_b128 v[126:129], v126 offset:57344
	s_waitcnt lgkmcnt(1)
	v_mfma_f32_32x32x16_bf16 v[80:95], v[122:125], v[118:121], v[80:95]
	v_mov_b32_e32 v122, v218
	s_waitcnt lgkmcnt(0)
	v_mfma_f32_32x32x16_bf16 v[64:79], v[126:129], v[118:121], v[64:79]
	ds_read_b128 v[118:121], v122 offset:49152
	ds_read_b128 v[122:125], v122 offset:57344
	s_waitcnt lgkmcnt(1)
	v_mfma_f32_32x32x16_bf16 v[80:95], v[118:121], v[114:117], v[80:95]
	v_mov_b32_e32 v118, v215
	s_waitcnt lgkmcnt(0)
	v_mfma_f32_32x32x16_bf16 v[64:79], v[122:125], v[114:117], v[64:79]
	ds_read_b128 v[114:117], v118 offset:49152
	ds_read_b128 v[118:121], v118 offset:57344
	v_mov_b32_e32 v122, v146
	v_mov_b32_e32 v123, v147
	s_waitcnt lgkmcnt(1)
	v_mfma_f32_32x32x16_bf16 v[80:95], v[114:117], v[110:113], v[80:95]
	v_mov_b32_e32 v114, v213
	s_waitcnt lgkmcnt(0)
	v_mfma_f32_32x32x16_bf16 v[64:79], v[118:121], v[110:113], v[64:79]
	ds_read_b128 v[110:113], v114 offset:49152
	ds_read_b128 v[114:117], v114 offset:57344
	v_mov_b32_e32 v118, v150
	v_mov_b32_e32 v119, v151
	v_mov_b32_e32 v120, v148
	v_mov_b32_e32 v121, v149
	s_waitcnt lgkmcnt(1)
	v_mfma_f32_32x32x16_bf16 v[80:95], v[110:113], v[106:109], v[80:95]
	v_mov_b32_e32 v110, v223
	s_waitcnt lgkmcnt(0)
	v_mfma_f32_32x32x16_bf16 v[64:79], v[114:117], v[106:109], v[64:79]
	ds_read_b128 v[106:109], v110 offset:49152
	ds_read_b128 v[110:113], v110 offset:57344
	v_mov_b32_e32 v114, v154
	v_mov_b32_e32 v115, v155
	v_mov_b32_e32 v116, v152
	v_mov_b32_e32 v117, v153
	s_waitcnt lgkmcnt(1)
	v_mfma_f32_32x32x16_bf16 v[80:95], v[106:109], v[102:105], v[80:95]
	v_mov_b32_e32 v106, v224
	s_waitcnt lgkmcnt(0)
	v_mfma_f32_32x32x16_bf16 v[64:79], v[110:113], v[102:105], v[64:79]
	ds_read_b128 v[102:105], v106 offset:49152
	ds_read_b128 v[106:109], v106 offset:57344
	v_mov_b32_e32 v110, v158
	v_mov_b32_e32 v111, v159
	v_mov_b32_e32 v112, v156
	v_mov_b32_e32 v113, v157
	s_waitcnt lgkmcnt(1)
	v_mfma_f32_32x32x16_bf16 v[80:95], v[102:105], v[98:101], v[80:95]
	s_waitcnt lgkmcnt(0)
	v_mfma_f32_32x32x16_bf16 v[64:79], v[106:109], v[98:101], v[64:79]
	v_add_f32_e32 v98, 0, v163
	v_add_f32_e32 v98, v177, v98
	v_add_f32_e32 v98, v164, v98
	v_add_f32_e32 v98, v229, v98
	v_add_f32_e32 v98, v176, v98
	v_add_f32_e32 v98, v230, v98
	v_add_f32_e32 v98, v165, v98
	v_add_f32_e32 v98, v175, v98
	v_add_f32_e32 v98, v171, v98
	v_add_f32_e32 v98, v173, v98
	v_add_f32_e32 v98, v172, v98
	v_add_f32_e32 v98, v174, v98
	v_mov_b32_e32 v108, v160
	v_add_f32_e32 v98, v167, v98
	v_mov_b32_e32 v109, v161
	v_add_f32_e32 v98, v169, v98
	v_add_f32_e32 v98, v168, v98
	v_add_f32_e32 v98, v170, v98
	v_add_f32_e32 v98, v108, v98
	v_add_f32_e32 v98, v109, v98
	v_add_f32_e32 v98, v110, v98
	v_add_f32_e32 v98, v111, v98
	v_add_f32_e32 v98, v112, v98
	v_add_f32_e32 v98, v113, v98
	v_add_f32_e32 v98, v114, v98
	v_add_f32_e32 v98, v115, v98
	v_add_f32_e32 v98, v116, v98
	v_add_f32_e32 v98, v117, v98
	v_add_f32_e32 v98, v118, v98
	v_add_f32_e32 v98, v119, v98
	v_add_f32_e32 v98, v120, v98
	v_add_f32_e32 v98, v121, v98
	v_add_f32_e32 v98, v122, v98
	v_add_f32_e32 v102, v123, v98
	v_mov_b32_e32 v103, v102
	v_cvt_pk_bf16_f32 v98, v163, v177
	v_cvt_pk_bf16_f32 v99, v164, v229
	v_cvt_pk_bf16_f32 v100, v176, v230
	v_cvt_pk_bf16_f32 v101, v165, v175
	s_nop 1
	v_permlane32_swap_b32_e32 v102, v103
	v_cvt_pk_bf16_f32 v104, v171, v173
	v_cvt_pk_bf16_f32 v105, v172, v174
	v_cvt_pk_bf16_f32 v106, v167, v169
	v_cvt_pk_bf16_f32 v107, v168, v170
	v_cvt_pk_bf16_f32 v108, v108, v109
	v_cvt_pk_bf16_f32 v109, v110, v111
	v_cvt_pk_bf16_f32 v110, v112, v113
	v_cvt_pk_bf16_f32 v111, v114, v115
	v_cvt_pk_bf16_f32 v112, v116, v117
	v_cvt_pk_bf16_f32 v113, v118, v119
	v_cvt_pk_bf16_f32 v114, v120, v121
	v_cvt_pk_bf16_f32 v115, v122, v123
	s_nop 0
	v_add_u32_e32 v132, s12, v212
	ds_read_b64_tr_b16 v[116:117], v132 offset:0
	ds_read_b64_tr_b16 v[118:119], v132 offset:0x800
	ds_read_b64_tr_b16 v[120:121], v132 offset:0x1000
	ds_read_b64_tr_b16 v[122:123], v132 offset:0x1800
	ds_read_b64_tr_b16 v[124:125], v132 offset:0x2000
	ds_read_b64_tr_b16 v[126:127], v132 offset:0x2800
	ds_read_b64_tr_b16 v[128:129], v132 offset:0x3000
	ds_read_b64_tr_b16 v[130:131], v132 offset:0x3800
	s_waitcnt lgkmcnt(0)
; #define RESC(a) do { if (__any((a) < 1.f)) { if (hi == 0) al_l[r32] = (a); asm volatile("s_waitcnt lgkmcnt(0)" ::: "memory"); \
;     _Pragma("unroll") for (int d = 0; d < 4; ++d) _Pragma("unroll") for (int r = 0; r < 16; ++r) o[d][r] *= al_l[crow(r, hi)]; } } while (0)
; __device__ __forceinline__ void attn_dense_body(const bf16_t* __restrict__ Qb, const bf16_t* __restrict__ Kh, const bf16_t* __restrict__ Vh,
;                                                 bf16_t* __restrict__ Ob, int seq, char* lds, int dry) {
;     ...
;     pv_d0(o, vb0 + ov, pa0, pa1, pa2, pa3); partialSM(pB0, pB1, m_reg, mnB, alB);
;     RESC(alB);
	s_nop 0
	v_mfma_f32_32x32x16_bf16 v[0:15], v[98:101], v[116:119], v[0:15]
	ds_read_b64_tr_b16 v[116:117], v132 offset:0x200
	ds_read_b64_tr_b16 v[118:119], v132 offset:0xa00
	v_mfma_f32_32x32x16_bf16 v[0:15], v[104:107], v[120:123], v[0:15]
	ds_read_b64_tr_b16 v[120:121], v132 offset:0x1200
	ds_read_b64_tr_b16 v[122:123], v132 offset:0x1a00
	v_mfma_f32_32x32x16_bf16 v[0:15], v[108:111], v[124:127], v[0:15]
	ds_read_b64_tr_b16 v[124:125], v132 offset:0x2200
	ds_read_b64_tr_b16 v[126:127], v132 offset:0x2a00
	v_mfma_f32_32x32x16_bf16 v[0:15], v[112:115], v[128:131], v[0:15]
	ds_read_b64_tr_b16 v[128:129], v132 offset:0x3200
	ds_read_b64_tr_b16 v[130:131], v132 offset:0x3a00
	s_waitcnt lgkmcnt(0)
	v_mfma_f32_32x32x16_bf16 v[48:63], v[98:101], v[116:119], v[48:63]
	ds_read_b64_tr_b16 v[116:117], v132 offset:0x400
	ds_read_b64_tr_b16 v[118:119], v132 offset:0xc00
	v_mfma_f32_32x32x16_bf16 v[48:63], v[104:107], v[120:123], v[48:63]
	ds_read_b64_tr_b16 v[120:121], v132 offset:0x1400
	ds_read_b64_tr_b16 v[122:123], v132 offset:0x1c00
	v_mfma_f32_32x32x16_bf16 v[48:63], v[108:111], v[124:127], v[48:63]
	ds_read_b64_tr_b16 v[124:125], v132 offset:0x2400
	ds_read_b64_tr_b16 v[126:127], v132 offset:0x2c00
	v_mfma_f32_32x32x16_bf16 v[48:63], v[112:115], v[128:131], v[48:63]
	ds_read_b64_tr_b16 v[128:129], v132 offset:0x3400
	ds_read_b64_tr_b16 v[130:131], v132 offset:0x3c00
	s_waitcnt lgkmcnt(0)
	v_mfma_f32_32x32x16_bf16 v[32:47], v[98:101], v[116:119], v[32:47]
	ds_read_b64_tr_b16 v[116:117], v132 offset:0x600
	ds_read_b64_tr_b16 v[118:119], v132 offset:0xe00
	v_mfma_f32_32x32x16_bf16 v[32:47], v[104:107], v[120:123], v[32:47]
	ds_read_b64_tr_b16 v[120:121], v132 offset:0x1600
	ds_read_b64_tr_b16 v[122:123], v132 offset:0x1e00
	v_mfma_f32_32x32x16_bf16 v[32:47], v[108:111], v[124:127], v[32:47]
	ds_read_b64_tr_b16 v[124:125], v132 offset:0x2600
	ds_read_b64_tr_b16 v[126:127], v132 offset:0x2e00
	v_mfma_f32_32x32x16_bf16 v[32:47], v[112:115], v[128:131], v[32:47]
	ds_read_b64_tr_b16 v[128:129], v132 offset:0x3600
	ds_read_b64_tr_b16 v[130:131], v132 offset:0x3e00
	s_waitcnt lgkmcnt(0)
	v_mfma_f32_32x32x16_bf16 v[16:31], v[98:101], v[116:119], v[16:31]
	v_max_f32_e32 v98, v81, v81
	v_max_f32_e32 v99, v80, v80
	v_max_f32_e32 v98, v99, v98
	v_max3_f32 v98, v98, v82, v83
	v_max3_f32 v98, v98, v84, v85
	v_max3_f32 v98, v98, v86, v87
	v_max3_f32 v98, v98, v88, v89
	v_max3_f32 v98, v98, v90, v91
	v_max3_f32 v98, v98, v92, v93
	v_mfma_f32_32x32x16_bf16 v[16:31], v[104:107], v[120:123], v[16:31]
	v_max3_f32 v98, v98, v94, v95
	v_max3_f32 v98, v98, v64, v65
	v_max3_f32 v98, v98, v66, v67
	v_max3_f32 v98, v98, v68, v69
	v_max3_f32 v98, v98, v70, v71
	v_max3_f32 v98, v98, v72, v73
	v_max3_f32 v98, v98, v74, v75
	v_max3_f32 v98, v98, v76, v77
	v_mfma_f32_32x32x16_bf16 v[16:31], v[108:111], v[124:127], v[16:31]
	v_max3_f32 v98, v98, v78, v79
	v_mov_b32_e32 v99, v98
	s_nop 1
	v_permlane32_swap_b32_e32 v98, v99
	v_max_f32_e32 v99, v99, v99
	v_max_f32_e32 v98, v98, v98
	v_max_f32_e32 v98, v98, v99
	v_sub_f32_e32 v99, v98, v166
	v_cmp_ge_f32_e32 vcc, s72, v99
	v_max_f32_e32 v99, v166, v166
	v_max_f32_e32 v99, v99, v98
	v_mfma_f32_32x32x16_bf16 v[16:31], v[112:115], v[128:131], v[16:31]
	v_sub_f32_e32 v98, v166, v99
	v_mul_f32_e32 v98, 0x3e0293ee, v98
	v_exp_f32_e32 v98, v98
	s_cmp_eq_u64 vcc, exec
	s_cselect_b64 s[8:9], -1, 0
	v_cndmask_b32_e64 v98, v98, 1.0, s[8:9]
	v_cmp_gt_f32_e32 vcc, 1.0, v98
	s_cbranch_vccz .LBB0_285
	s_and_saveexec_b64 s[10:11], s[6:7]
	ds_write_b32 v209, v98 offset:128
	s_or_b64 exec, exec, s[10:11]
	s_waitcnt lgkmcnt(0)
	v_add_u32_e32 v100, v179, v96
	ds_read_b128 v[104:107], v100 offset:224
	ds_read_b128 v[108:111], v100 offset:192
	ds_read_b128 v[112:115], v100 offset:160
	ds_read_b128 v[116:119], v100 offset:128
	s_waitcnt lgkmcnt(3)
	v_pk_mul_f32 v[12:13], v[12:13], v[104:105]
	s_waitcnt lgkmcnt(2)
	v_pk_mul_f32 v[8:9], v[8:9], v[108:109]
	s_waitcnt lgkmcnt(1)
	v_pk_mul_f32 v[4:5], v[4:5], v[112:113]
	v_pk_mul_f32 v[14:15], v[14:15], v[106:107]
	v_pk_mul_f32 v[10:11], v[10:11], v[110:111]
	v_pk_mul_f32 v[6:7], v[6:7], v[114:115]
	s_waitcnt lgkmcnt(0)
	v_pk_mul_f32 v[2:3], v[2:3], v[118:119]
	v_pk_mul_f32 v[0:1], v[0:1], v[116:117]
	v_pk_mul_f32 v[60:61], v[60:61], v[104:105]
	v_pk_mul_f32 v[56:57], v[56:57], v[108:109]
	v_pk_mul_f32 v[52:53], v[52:53], v[112:113]
	v_pk_mul_f32 v[62:63], v[62:63], v[106:107]
	v_pk_mul_f32 v[58:59], v[58:59], v[110:111]
	v_pk_mul_f32 v[54:55], v[54:55], v[114:115]
	v_pk_mul_f32 v[50:51], v[50:51], v[118:119]
	v_pk_mul_f32 v[48:49], v[48:49], v[116:117]
	v_pk_mul_f32 v[44:45], v[44:45], v[104:105]
	v_pk_mul_f32 v[40:41], v[40:41], v[108:109]
	v_pk_mul_f32 v[36:37], v[36:37], v[112:113]
	v_pk_mul_f32 v[46:47], v[46:47], v[106:107]
	v_pk_mul_f32 v[42:43], v[42:43], v[110:111]
	v_pk_mul_f32 v[38:39], v[38:39], v[114:115]
	v_pk_mul_f32 v[34:35], v[34:35], v[118:119]
	v_pk_mul_f32 v[32:33], v[32:33], v[116:117]
	v_pk_mul_f32 v[28:29], v[28:29], v[104:105]
	v_pk_mul_f32 v[24:25], v[24:25], v[108:109]
	v_pk_mul_f32 v[20:21], v[20:21], v[112:113]
	v_pk_mul_f32 v[30:31], v[30:31], v[106:107]
	v_pk_mul_f32 v[26:27], v[26:27], v[110:111]
	v_pk_mul_f32 v[22:23], v[22:23], v[114:115]
	v_pk_mul_f32 v[18:19], v[18:19], v[118:119]
	v_pk_mul_f32 v[16:17], v[16:17], v[116:117]
